# ffn_in: own SwiGLU epilogue for both tiles, adjacent 16-column blocks paired with permlane16_swap into 16-byte stores (half the store instructions)
# speedup vs baseline: 1.0198x; 1.0125x over previous
.Lf2_k:
	s_waitcnt vmcnt(0)
	s_barrier
	s_add_i32 m0, s64, 0xc000
	s_nop 0
	global_load_lds_dwordx4 v76, s[58:59]
	s_add_i32 m0, s64, 0xd000
	s_nop 0
	global_load_lds_dwordx4 v77, s[58:59]
	s_add_i32 m0, s64, 0xe000
	s_nop 0
	global_load_lds_dwordx4 v78, s[58:59]
	s_add_i32 m0, s64, 0xf000
	s_nop 0
	global_load_lds_dwordx4 v79, s[58:59]
	s_add_u32 s58, s58, 0x80
	s_addc_u32 s59, s59, 0
	ds_read_b128 v[148:151], v80 offset:0
	ds_read_b128 v[152:155], v80 offset:2048
	ds_read_b128 v[156:159], v80 offset:4096
	ds_read_b128 v[160:163], v80 offset:6144
	ds_read_b128 v[188:191], v144 offset:32768
	ds_read_b128 v[192:195], v144 offset:34816
	ds_read_b128 v[208:211], v144 offset:36864
	ds_read_b128 v[212:215], v144 offset:38912
	ds_read_b128 v[164:167], v80 offset:16384
	ds_read_b128 v[168:171], v80 offset:18432
	ds_read_b128 v[174:177], v80 offset:20480
	ds_read_b128 v[182:185], v80 offset:22528
	s_setprio 1
	s_waitcnt lgkmcnt(4)
	v_mfma_f32_16x16x32_bf16 v[62:65], v[188:191], v[148:151], v[62:65]
	v_mfma_f32_16x16x32_bf16 v[54:57], v[192:195], v[148:151], v[54:57]
	v_mfma_f32_16x16x32_bf16 v[58:61], v[208:211], v[148:151], v[58:61]
	v_mfma_f32_16x16x32_bf16 v[50:53], v[212:215], v[148:151], v[50:53]
	v_mfma_f32_16x16x32_bf16 v[46:49], v[188:191], v[152:155], v[46:49]
	v_mfma_f32_16x16x32_bf16 v[38:41], v[192:195], v[152:155], v[38:41]
	v_mfma_f32_16x16x32_bf16 v[42:45], v[208:211], v[152:155], v[42:45]
	v_mfma_f32_16x16x32_bf16 v[34:37], v[212:215], v[152:155], v[34:37]
	v_mfma_f32_16x16x32_bf16 v[30:33], v[188:191], v[156:159], v[30:33]
	v_mfma_f32_16x16x32_bf16 v[22:25], v[192:195], v[156:159], v[22:25]
	v_mfma_f32_16x16x32_bf16 v[26:29], v[208:211], v[156:159], v[26:29]
	v_mfma_f32_16x16x32_bf16 v[18:21], v[212:215], v[156:159], v[18:21]
	v_mfma_f32_16x16x32_bf16 v[14:17], v[188:191], v[160:163], v[14:17]
	v_mfma_f32_16x16x32_bf16 v[6:9], v[192:195], v[160:163], v[6:9]
	v_mfma_f32_16x16x32_bf16 v[10:13], v[208:211], v[160:163], v[10:13]
	v_mfma_f32_16x16x32_bf16 v[2:5], v[212:215], v[160:163], v[2:5]
	s_waitcnt lgkmcnt(0)
	v_mfma_f32_16x16x32_bf16 v[66:69], v[188:191], v[164:167], v[66:69]
	v_mfma_f32_16x16x32_bf16 v[70:73], v[192:195], v[164:167], v[70:73]
	v_mfma_f32_16x16x32_bf16 v[82:85], v[208:211], v[164:167], v[82:85]
	v_mfma_f32_16x16x32_bf16 v[86:89], v[212:215], v[164:167], v[86:89]
	v_mfma_f32_16x16x32_bf16 v[90:93], v[188:191], v[168:171], v[90:93]
	v_mfma_f32_16x16x32_bf16 v[94:97], v[192:195], v[168:171], v[94:97]
	v_mfma_f32_16x16x32_bf16 v[98:101], v[208:211], v[168:171], v[98:101]
	v_mfma_f32_16x16x32_bf16 v[102:105], v[212:215], v[168:171], v[102:105]
	v_mfma_f32_16x16x32_bf16 v[106:109], v[188:191], v[174:177], v[106:109]
	v_mfma_f32_16x16x32_bf16 v[110:113], v[192:195], v[174:177], v[110:113]
	v_mfma_f32_16x16x32_bf16 v[114:117], v[208:211], v[174:177], v[114:117]
	v_mfma_f32_16x16x32_bf16 v[118:121], v[212:215], v[174:177], v[118:121]
	v_mfma_f32_16x16x32_bf16 v[122:125], v[188:191], v[182:185], v[122:125]
	v_mfma_f32_16x16x32_bf16 v[126:129], v[192:195], v[182:185], v[126:129]
	v_mfma_f32_16x16x32_bf16 v[136:139], v[208:211], v[182:185], v[136:139]
	v_mfma_f32_16x16x32_bf16 v[140:143], v[212:215], v[182:185], v[140:143]
	s_setprio 0
	ds_read_b128 v[148:151], v81 offset:0
	ds_read_b128 v[152:155], v81 offset:2048
	ds_read_b128 v[156:159], v81 offset:4096
	ds_read_b128 v[160:163], v81 offset:6144
	ds_read_b128 v[188:191], v145 offset:32768
	ds_read_b128 v[192:195], v145 offset:34816
	ds_read_b128 v[208:211], v145 offset:36864
	ds_read_b128 v[212:215], v145 offset:38912
	ds_read_b128 v[164:167], v81 offset:16384
	ds_read_b128 v[168:171], v81 offset:18432
	ds_read_b128 v[174:177], v81 offset:20480
	ds_read_b128 v[182:185], v81 offset:22528
	s_waitcnt lgkmcnt(0)
	s_barrier
	s_add_i32 m0, s64, 0x0
	s_nop 0
	global_load_lds_dwordx4 v76, s[50:51]
	s_add_i32 m0, s64, 0x1000
	s_nop 0
	global_load_lds_dwordx4 v77, s[50:51]
	s_add_i32 m0, s64, 0x2000
	s_nop 0
	global_load_lds_dwordx4 v78, s[50:51]
	s_add_i32 m0, s64, 0x3000
	s_nop 0
	global_load_lds_dwordx4 v79, s[50:51]
	s_add_i32 m0, s64, 0x4000
	s_nop 0
	global_load_lds_dwordx4 v76, s[52:53]
	s_add_i32 m0, s64, 0x5000
	s_nop 0
	global_load_lds_dwordx4 v77, s[52:53]
	s_add_i32 m0, s64, 0x6000
	s_nop 0
	global_load_lds_dwordx4 v78, s[52:53]
	s_add_i32 m0, s64, 0x7000
	s_nop 0
	global_load_lds_dwordx4 v79, s[52:53]
	s_add_u32 s50, s50, 0x80
	s_addc_u32 s51, s51, 0
	s_add_u32 s52, s52, 0x80
	s_addc_u32 s53, s53, 0
	s_setprio 1
	v_mfma_f32_16x16x32_bf16 v[62:65], v[188:191], v[148:151], v[62:65]
	v_mfma_f32_16x16x32_bf16 v[54:57], v[192:195], v[148:151], v[54:57]
	v_mfma_f32_16x16x32_bf16 v[58:61], v[208:211], v[148:151], v[58:61]
	v_mfma_f32_16x16x32_bf16 v[50:53], v[212:215], v[148:151], v[50:53]
	v_mfma_f32_16x16x32_bf16 v[46:49], v[188:191], v[152:155], v[46:49]
	v_mfma_f32_16x16x32_bf16 v[38:41], v[192:195], v[152:155], v[38:41]
	v_mfma_f32_16x16x32_bf16 v[42:45], v[208:211], v[152:155], v[42:45]
	v_mfma_f32_16x16x32_bf16 v[34:37], v[212:215], v[152:155], v[34:37]
	v_mfma_f32_16x16x32_bf16 v[30:33], v[188:191], v[156:159], v[30:33]
	v_mfma_f32_16x16x32_bf16 v[22:25], v[192:195], v[156:159], v[22:25]
	v_mfma_f32_16x16x32_bf16 v[26:29], v[208:211], v[156:159], v[26:29]
	v_mfma_f32_16x16x32_bf16 v[18:21], v[212:215], v[156:159], v[18:21]
	v_mfma_f32_16x16x32_bf16 v[14:17], v[188:191], v[160:163], v[14:17]
	v_mfma_f32_16x16x32_bf16 v[6:9], v[192:195], v[160:163], v[6:9]
	v_mfma_f32_16x16x32_bf16 v[10:13], v[208:211], v[160:163], v[10:13]
	v_mfma_f32_16x16x32_bf16 v[2:5], v[212:215], v[160:163], v[2:5]
	v_mfma_f32_16x16x32_bf16 v[66:69], v[188:191], v[164:167], v[66:69]
	v_mfma_f32_16x16x32_bf16 v[70:73], v[192:195], v[164:167], v[70:73]
	v_mfma_f32_16x16x32_bf16 v[82:85], v[208:211], v[164:167], v[82:85]
	v_mfma_f32_16x16x32_bf16 v[86:89], v[212:215], v[164:167], v[86:89]
	v_mfma_f32_16x16x32_bf16 v[90:93], v[188:191], v[168:171], v[90:93]
	v_mfma_f32_16x16x32_bf16 v[94:97], v[192:195], v[168:171], v[94:97]
	v_mfma_f32_16x16x32_bf16 v[98:101], v[208:211], v[168:171], v[98:101]
	v_mfma_f32_16x16x32_bf16 v[102:105], v[212:215], v[168:171], v[102:105]
	v_mfma_f32_16x16x32_bf16 v[106:109], v[188:191], v[174:177], v[106:109]
	v_mfma_f32_16x16x32_bf16 v[110:113], v[192:195], v[174:177], v[110:113]
	v_mfma_f32_16x16x32_bf16 v[114:117], v[208:211], v[174:177], v[114:117]
	v_mfma_f32_16x16x32_bf16 v[118:121], v[212:215], v[174:177], v[118:121]
	v_mfma_f32_16x16x32_bf16 v[122:125], v[188:191], v[182:185], v[122:125]
	v_mfma_f32_16x16x32_bf16 v[126:129], v[192:195], v[182:185], v[126:129]
	v_mfma_f32_16x16x32_bf16 v[136:139], v[208:211], v[182:185], v[136:139]
	v_mfma_f32_16x16x32_bf16 v[140:143], v[212:215], v[182:185], v[140:143]
	s_setprio 0
	s_waitcnt vmcnt(0)
	s_barrier
	s_add_i32 m0, s64, 0x8000
	s_nop 0
	global_load_lds_dwordx4 v76, s[58:59]
	s_add_i32 m0, s64, 0x9000
	s_nop 0
	global_load_lds_dwordx4 v77, s[58:59]
	s_add_i32 m0, s64, 0xa000
	s_nop 0
	global_load_lds_dwordx4 v78, s[58:59]
	s_add_i32 m0, s64, 0xb000
	s_nop 0
	global_load_lds_dwordx4 v79, s[58:59]
	s_add_u32 s58, s58, 0x80
	s_addc_u32 s59, s59, 0
	ds_read_b128 v[148:151], v80 offset:0
	ds_read_b128 v[152:155], v80 offset:2048
	ds_read_b128 v[156:159], v80 offset:4096
	ds_read_b128 v[160:163], v80 offset:6144
	ds_read_b128 v[188:191], v144 offset:49152
	ds_read_b128 v[192:195], v144 offset:51200
	ds_read_b128 v[208:211], v144 offset:53248
	ds_read_b128 v[212:215], v144 offset:55296
	ds_read_b128 v[164:167], v80 offset:16384
	ds_read_b128 v[168:171], v80 offset:18432
	ds_read_b128 v[174:177], v80 offset:20480
	ds_read_b128 v[182:185], v80 offset:22528
	s_setprio 1
	s_waitcnt lgkmcnt(4)
	v_mfma_f32_16x16x32_bf16 v[62:65], v[188:191], v[148:151], v[62:65]
	v_mfma_f32_16x16x32_bf16 v[54:57], v[192:195], v[148:151], v[54:57]
	v_mfma_f32_16x16x32_bf16 v[58:61], v[208:211], v[148:151], v[58:61]
	v_mfma_f32_16x16x32_bf16 v[50:53], v[212:215], v[148:151], v[50:53]
	v_mfma_f32_16x16x32_bf16 v[46:49], v[188:191], v[152:155], v[46:49]
	v_mfma_f32_16x16x32_bf16 v[38:41], v[192:195], v[152:155], v[38:41]
	v_mfma_f32_16x16x32_bf16 v[42:45], v[208:211], v[152:155], v[42:45]
	v_mfma_f32_16x16x32_bf16 v[34:37], v[212:215], v[152:155], v[34:37]
	v_mfma_f32_16x16x32_bf16 v[30:33], v[188:191], v[156:159], v[30:33]
	v_mfma_f32_16x16x32_bf16 v[22:25], v[192:195], v[156:159], v[22:25]
	v_mfma_f32_16x16x32_bf16 v[26:29], v[208:211], v[156:159], v[26:29]
	v_mfma_f32_16x16x32_bf16 v[18:21], v[212:215], v[156:159], v[18:21]
	v_mfma_f32_16x16x32_bf16 v[14:17], v[188:191], v[160:163], v[14:17]
	v_mfma_f32_16x16x32_bf16 v[6:9], v[192:195], v[160:163], v[6:9]
	v_mfma_f32_16x16x32_bf16 v[10:13], v[208:211], v[160:163], v[10:13]
	v_mfma_f32_16x16x32_bf16 v[2:5], v[212:215], v[160:163], v[2:5]
	s_waitcnt lgkmcnt(0)
	v_mfma_f32_16x16x32_bf16 v[66:69], v[188:191], v[164:167], v[66:69]
	v_mfma_f32_16x16x32_bf16 v[70:73], v[192:195], v[164:167], v[70:73]
	v_mfma_f32_16x16x32_bf16 v[82:85], v[208:211], v[164:167], v[82:85]
	v_mfma_f32_16x16x32_bf16 v[86:89], v[212:215], v[164:167], v[86:89]
	v_mfma_f32_16x16x32_bf16 v[90:93], v[188:191], v[168:171], v[90:93]
	v_mfma_f32_16x16x32_bf16 v[94:97], v[192:195], v[168:171], v[94:97]
	v_mfma_f32_16x16x32_bf16 v[98:101], v[208:211], v[168:171], v[98:101]
	v_mfma_f32_16x16x32_bf16 v[102:105], v[212:215], v[168:171], v[102:105]
	v_mfma_f32_16x16x32_bf16 v[106:109], v[188:191], v[174:177], v[106:109]
	v_mfma_f32_16x16x32_bf16 v[110:113], v[192:195], v[174:177], v[110:113]
	v_mfma_f32_16x16x32_bf16 v[114:117], v[208:211], v[174:177], v[114:117]
	v_mfma_f32_16x16x32_bf16 v[118:121], v[212:215], v[174:177], v[118:121]
	v_mfma_f32_16x16x32_bf16 v[122:125], v[188:191], v[182:185], v[122:125]
	v_mfma_f32_16x16x32_bf16 v[126:129], v[192:195], v[182:185], v[126:129]
	v_mfma_f32_16x16x32_bf16 v[136:139], v[208:211], v[182:185], v[136:139]
	v_mfma_f32_16x16x32_bf16 v[140:143], v[212:215], v[182:185], v[140:143]
	s_setprio 0
	ds_read_b128 v[148:151], v81 offset:0
	ds_read_b128 v[152:155], v81 offset:2048
	ds_read_b128 v[156:159], v81 offset:4096
	ds_read_b128 v[160:163], v81 offset:6144
	ds_read_b128 v[188:191], v145 offset:49152
	ds_read_b128 v[192:195], v145 offset:51200
	ds_read_b128 v[208:211], v145 offset:53248
	ds_read_b128 v[212:215], v145 offset:55296
	ds_read_b128 v[164:167], v81 offset:16384
	ds_read_b128 v[168:171], v81 offset:18432
	ds_read_b128 v[174:177], v81 offset:20480
	ds_read_b128 v[182:185], v81 offset:22528
	s_waitcnt lgkmcnt(0)
	s_barrier
	s_add_i32 m0, s64, 0x0
	s_nop 0
	global_load_lds_dwordx4 v76, s[50:51]
	s_add_i32 m0, s64, 0x1000
	s_nop 0
	global_load_lds_dwordx4 v77, s[50:51]
	s_add_i32 m0, s64, 0x2000
	s_nop 0
	global_load_lds_dwordx4 v78, s[50:51]
	s_add_i32 m0, s64, 0x3000
	s_nop 0
	global_load_lds_dwordx4 v79, s[50:51]
	s_add_i32 m0, s64, 0x4000
	s_nop 0
	global_load_lds_dwordx4 v76, s[52:53]
	s_add_i32 m0, s64, 0x5000
	s_nop 0
	global_load_lds_dwordx4 v77, s[52:53]
	s_add_i32 m0, s64, 0x6000
	s_nop 0
	global_load_lds_dwordx4 v78, s[52:53]
	s_add_i32 m0, s64, 0x7000
	s_nop 0
	global_load_lds_dwordx4 v79, s[52:53]
	s_add_u32 s50, s50, 0x80
	s_addc_u32 s51, s51, 0
	s_add_u32 s52, s52, 0x80
	s_addc_u32 s53, s53, 0
	s_setprio 1
	v_mfma_f32_16x16x32_bf16 v[62:65], v[188:191], v[148:151], v[62:65]
	v_mfma_f32_16x16x32_bf16 v[54:57], v[192:195], v[148:151], v[54:57]
	v_mfma_f32_16x16x32_bf16 v[58:61], v[208:211], v[148:151], v[58:61]
	v_mfma_f32_16x16x32_bf16 v[50:53], v[212:215], v[148:151], v[50:53]
	v_mfma_f32_16x16x32_bf16 v[46:49], v[188:191], v[152:155], v[46:49]
	v_mfma_f32_16x16x32_bf16 v[38:41], v[192:195], v[152:155], v[38:41]
	v_mfma_f32_16x16x32_bf16 v[42:45], v[208:211], v[152:155], v[42:45]
	v_mfma_f32_16x16x32_bf16 v[34:37], v[212:215], v[152:155], v[34:37]
	v_mfma_f32_16x16x32_bf16 v[30:33], v[188:191], v[156:159], v[30:33]
	v_mfma_f32_16x16x32_bf16 v[22:25], v[192:195], v[156:159], v[22:25]
	v_mfma_f32_16x16x32_bf16 v[26:29], v[208:211], v[156:159], v[26:29]
	v_mfma_f32_16x16x32_bf16 v[18:21], v[212:215], v[156:159], v[18:21]
	v_mfma_f32_16x16x32_bf16 v[14:17], v[188:191], v[160:163], v[14:17]
	v_mfma_f32_16x16x32_bf16 v[6:9], v[192:195], v[160:163], v[6:9]
	v_mfma_f32_16x16x32_bf16 v[10:13], v[208:211], v[160:163], v[10:13]
	v_mfma_f32_16x16x32_bf16 v[2:5], v[212:215], v[160:163], v[2:5]
	v_mfma_f32_16x16x32_bf16 v[66:69], v[188:191], v[164:167], v[66:69]
	v_mfma_f32_16x16x32_bf16 v[70:73], v[192:195], v[164:167], v[70:73]
	v_mfma_f32_16x16x32_bf16 v[82:85], v[208:211], v[164:167], v[82:85]
	v_mfma_f32_16x16x32_bf16 v[86:89], v[212:215], v[164:167], v[86:89]
	v_mfma_f32_16x16x32_bf16 v[90:93], v[188:191], v[168:171], v[90:93]
	v_mfma_f32_16x16x32_bf16 v[94:97], v[192:195], v[168:171], v[94:97]
	v_mfma_f32_16x16x32_bf16 v[98:101], v[208:211], v[168:171], v[98:101]
	v_mfma_f32_16x16x32_bf16 v[102:105], v[212:215], v[168:171], v[102:105]
	v_mfma_f32_16x16x32_bf16 v[106:109], v[188:191], v[174:177], v[106:109]
	v_mfma_f32_16x16x32_bf16 v[110:113], v[192:195], v[174:177], v[110:113]
	v_mfma_f32_16x16x32_bf16 v[114:117], v[208:211], v[174:177], v[114:117]
	v_mfma_f32_16x16x32_bf16 v[118:121], v[212:215], v[174:177], v[118:121]
	v_mfma_f32_16x16x32_bf16 v[122:125], v[188:191], v[182:185], v[122:125]
	v_mfma_f32_16x16x32_bf16 v[126:129], v[192:195], v[182:185], v[126:129]
	v_mfma_f32_16x16x32_bf16 v[136:139], v[208:211], v[182:185], v[136:139]
	v_mfma_f32_16x16x32_bf16 v[140:143], v[212:215], v[182:185], v[140:143]
	s_setprio 0
	s_add_i32 s65, s65, -1
	s_cmp_lg_u32 s65, 0
	s_cbranch_scc1 .Lf2_k
	s_waitcnt vmcnt(0)
	s_barrier
	s_add_i32 m0, s64, 0xc000
	s_nop 0
	global_load_lds_dwordx4 v76, s[58:59]
	s_add_i32 m0, s64, 0xd000
	s_nop 0
	global_load_lds_dwordx4 v77, s[58:59]
	s_add_i32 m0, s64, 0xe000
	s_nop 0
	global_load_lds_dwordx4 v78, s[58:59]
	s_add_i32 m0, s64, 0xf000
	s_nop 0
	global_load_lds_dwordx4 v79, s[58:59]
	s_add_u32 s58, s58, 0x80
	s_addc_u32 s59, s59, 0
	ds_read_b128 v[148:151], v80 offset:0
	ds_read_b128 v[152:155], v80 offset:2048
	ds_read_b128 v[156:159], v80 offset:4096
	ds_read_b128 v[160:163], v80 offset:6144
	ds_read_b128 v[188:191], v144 offset:32768
	ds_read_b128 v[192:195], v144 offset:34816
	ds_read_b128 v[208:211], v144 offset:36864
	ds_read_b128 v[212:215], v144 offset:38912
	ds_read_b128 v[164:167], v80 offset:16384
	ds_read_b128 v[168:171], v80 offset:18432
	ds_read_b128 v[174:177], v80 offset:20480
	ds_read_b128 v[182:185], v80 offset:22528
	s_setprio 1
	s_waitcnt lgkmcnt(4)
	v_mfma_f32_16x16x32_bf16 v[62:65], v[188:191], v[148:151], v[62:65]
	v_mfma_f32_16x16x32_bf16 v[54:57], v[192:195], v[148:151], v[54:57]
	v_mfma_f32_16x16x32_bf16 v[58:61], v[208:211], v[148:151], v[58:61]
	v_mfma_f32_16x16x32_bf16 v[50:53], v[212:215], v[148:151], v[50:53]
	v_mfma_f32_16x16x32_bf16 v[46:49], v[188:191], v[152:155], v[46:49]
	v_mfma_f32_16x16x32_bf16 v[38:41], v[192:195], v[152:155], v[38:41]
	v_mfma_f32_16x16x32_bf16 v[42:45], v[208:211], v[152:155], v[42:45]
	v_mfma_f32_16x16x32_bf16 v[34:37], v[212:215], v[152:155], v[34:37]
	v_mfma_f32_16x16x32_bf16 v[30:33], v[188:191], v[156:159], v[30:33]
	v_mfma_f32_16x16x32_bf16 v[22:25], v[192:195], v[156:159], v[22:25]
	v_mfma_f32_16x16x32_bf16 v[26:29], v[208:211], v[156:159], v[26:29]
	v_mfma_f32_16x16x32_bf16 v[18:21], v[212:215], v[156:159], v[18:21]
	v_mfma_f32_16x16x32_bf16 v[14:17], v[188:191], v[160:163], v[14:17]
	v_mfma_f32_16x16x32_bf16 v[6:9], v[192:195], v[160:163], v[6:9]
	v_mfma_f32_16x16x32_bf16 v[10:13], v[208:211], v[160:163], v[10:13]
	v_mfma_f32_16x16x32_bf16 v[2:5], v[212:215], v[160:163], v[2:5]
	s_waitcnt lgkmcnt(0)
	v_mfma_f32_16x16x32_bf16 v[66:69], v[188:191], v[164:167], v[66:69]
	v_mfma_f32_16x16x32_bf16 v[70:73], v[192:195], v[164:167], v[70:73]
	v_mfma_f32_16x16x32_bf16 v[82:85], v[208:211], v[164:167], v[82:85]
	v_mfma_f32_16x16x32_bf16 v[86:89], v[212:215], v[164:167], v[86:89]
	v_mfma_f32_16x16x32_bf16 v[90:93], v[188:191], v[168:171], v[90:93]
	v_mfma_f32_16x16x32_bf16 v[94:97], v[192:195], v[168:171], v[94:97]
	v_mfma_f32_16x16x32_bf16 v[98:101], v[208:211], v[168:171], v[98:101]
	v_mfma_f32_16x16x32_bf16 v[102:105], v[212:215], v[168:171], v[102:105]
	v_mfma_f32_16x16x32_bf16 v[106:109], v[188:191], v[174:177], v[106:109]
	v_mfma_f32_16x16x32_bf16 v[110:113], v[192:195], v[174:177], v[110:113]
	v_mfma_f32_16x16x32_bf16 v[114:117], v[208:211], v[174:177], v[114:117]
	v_mfma_f32_16x16x32_bf16 v[118:121], v[212:215], v[174:177], v[118:121]
	v_mfma_f32_16x16x32_bf16 v[122:125], v[188:191], v[182:185], v[122:125]
	v_mfma_f32_16x16x32_bf16 v[126:129], v[192:195], v[182:185], v[126:129]
	v_mfma_f32_16x16x32_bf16 v[136:139], v[208:211], v[182:185], v[136:139]
	v_mfma_f32_16x16x32_bf16 v[140:143], v[212:215], v[182:185], v[140:143]
	s_setprio 0
	ds_read_b128 v[148:151], v81 offset:0
	ds_read_b128 v[152:155], v81 offset:2048
	ds_read_b128 v[156:159], v81 offset:4096
	ds_read_b128 v[160:163], v81 offset:6144
	ds_read_b128 v[188:191], v145 offset:32768
	ds_read_b128 v[192:195], v145 offset:34816
	ds_read_b128 v[208:211], v145 offset:36864
	ds_read_b128 v[212:215], v145 offset:38912
	ds_read_b128 v[164:167], v81 offset:16384
	ds_read_b128 v[168:171], v81 offset:18432
	ds_read_b128 v[174:177], v81 offset:20480
	ds_read_b128 v[182:185], v81 offset:22528
	s_waitcnt lgkmcnt(0)
	s_barrier
	s_add_i32 m0, s64, 0x0
	s_nop 0
	global_load_lds_dwordx4 v76, s[50:51]
	s_add_i32 m0, s64, 0x1000
	s_nop 0
	global_load_lds_dwordx4 v77, s[50:51]
	s_add_i32 m0, s64, 0x2000
	s_nop 0
	global_load_lds_dwordx4 v78, s[50:51]
	s_add_i32 m0, s64, 0x3000
	s_nop 0
	global_load_lds_dwordx4 v79, s[50:51]
	s_add_i32 m0, s64, 0x4000
	s_nop 0
	global_load_lds_dwordx4 v76, s[52:53]
	s_add_i32 m0, s64, 0x5000
	s_nop 0
	global_load_lds_dwordx4 v77, s[52:53]
	s_add_i32 m0, s64, 0x6000
	s_nop 0
	global_load_lds_dwordx4 v78, s[52:53]
	s_add_i32 m0, s64, 0x7000
	s_nop 0
	global_load_lds_dwordx4 v79, s[52:53]
	s_add_u32 s50, s50, 0x80
	s_addc_u32 s51, s51, 0
	s_add_u32 s52, s52, 0x80
	s_addc_u32 s53, s53, 0
	s_setprio 1
	v_mfma_f32_16x16x32_bf16 v[62:65], v[188:191], v[148:151], v[62:65]
	v_mfma_f32_16x16x32_bf16 v[54:57], v[192:195], v[148:151], v[54:57]
	v_mfma_f32_16x16x32_bf16 v[58:61], v[208:211], v[148:151], v[58:61]
	v_mfma_f32_16x16x32_bf16 v[50:53], v[212:215], v[148:151], v[50:53]
	v_mfma_f32_16x16x32_bf16 v[46:49], v[188:191], v[152:155], v[46:49]
	v_mfma_f32_16x16x32_bf16 v[38:41], v[192:195], v[152:155], v[38:41]
	v_mfma_f32_16x16x32_bf16 v[42:45], v[208:211], v[152:155], v[42:45]
	v_mfma_f32_16x16x32_bf16 v[34:37], v[212:215], v[152:155], v[34:37]
	v_mfma_f32_16x16x32_bf16 v[30:33], v[188:191], v[156:159], v[30:33]
	v_mfma_f32_16x16x32_bf16 v[22:25], v[192:195], v[156:159], v[22:25]
	v_mfma_f32_16x16x32_bf16 v[26:29], v[208:211], v[156:159], v[26:29]
	v_mfma_f32_16x16x32_bf16 v[18:21], v[212:215], v[156:159], v[18:21]
	v_mfma_f32_16x16x32_bf16 v[14:17], v[188:191], v[160:163], v[14:17]
	v_mfma_f32_16x16x32_bf16 v[6:9], v[192:195], v[160:163], v[6:9]
	v_mfma_f32_16x16x32_bf16 v[10:13], v[208:211], v[160:163], v[10:13]
	v_mfma_f32_16x16x32_bf16 v[2:5], v[212:215], v[160:163], v[2:5]
	v_mfma_f32_16x16x32_bf16 v[66:69], v[188:191], v[164:167], v[66:69]
	v_mfma_f32_16x16x32_bf16 v[70:73], v[192:195], v[164:167], v[70:73]
	v_mfma_f32_16x16x32_bf16 v[82:85], v[208:211], v[164:167], v[82:85]
	v_mfma_f32_16x16x32_bf16 v[86:89], v[212:215], v[164:167], v[86:89]
	v_mfma_f32_16x16x32_bf16 v[90:93], v[188:191], v[168:171], v[90:93]
	v_mfma_f32_16x16x32_bf16 v[94:97], v[192:195], v[168:171], v[94:97]
	v_mfma_f32_16x16x32_bf16 v[98:101], v[208:211], v[168:171], v[98:101]
	v_mfma_f32_16x16x32_bf16 v[102:105], v[212:215], v[168:171], v[102:105]
	v_mfma_f32_16x16x32_bf16 v[106:109], v[188:191], v[174:177], v[106:109]
	v_mfma_f32_16x16x32_bf16 v[110:113], v[192:195], v[174:177], v[110:113]
	v_mfma_f32_16x16x32_bf16 v[114:117], v[208:211], v[174:177], v[114:117]
	v_mfma_f32_16x16x32_bf16 v[118:121], v[212:215], v[174:177], v[118:121]
	v_mfma_f32_16x16x32_bf16 v[122:125], v[188:191], v[182:185], v[122:125]
	v_mfma_f32_16x16x32_bf16 v[126:129], v[192:195], v[182:185], v[126:129]
	v_mfma_f32_16x16x32_bf16 v[136:139], v[208:211], v[182:185], v[136:139]
	v_mfma_f32_16x16x32_bf16 v[140:143], v[212:215], v[182:185], v[140:143]
	s_setprio 0
	s_waitcnt vmcnt(0)
	s_barrier
	ds_read_b128 v[148:151], v80 offset:0
	ds_read_b128 v[152:155], v80 offset:2048
	ds_read_b128 v[156:159], v80 offset:4096
	ds_read_b128 v[160:163], v80 offset:6144
	ds_read_b128 v[188:191], v144 offset:49152
	ds_read_b128 v[192:195], v144 offset:51200
	ds_read_b128 v[208:211], v144 offset:53248
	ds_read_b128 v[212:215], v144 offset:55296
	ds_read_b128 v[164:167], v80 offset:16384
	ds_read_b128 v[168:171], v80 offset:18432
	ds_read_b128 v[174:177], v80 offset:20480
	ds_read_b128 v[182:185], v80 offset:22528
	s_setprio 1
	s_waitcnt lgkmcnt(4)
	v_mfma_f32_16x16x32_bf16 v[62:65], v[188:191], v[148:151], v[62:65]
	v_mfma_f32_16x16x32_bf16 v[54:57], v[192:195], v[148:151], v[54:57]
	v_mfma_f32_16x16x32_bf16 v[58:61], v[208:211], v[148:151], v[58:61]
	v_mfma_f32_16x16x32_bf16 v[50:53], v[212:215], v[148:151], v[50:53]
	v_mfma_f32_16x16x32_bf16 v[46:49], v[188:191], v[152:155], v[46:49]
	v_mfma_f32_16x16x32_bf16 v[38:41], v[192:195], v[152:155], v[38:41]
	v_mfma_f32_16x16x32_bf16 v[42:45], v[208:211], v[152:155], v[42:45]
	v_mfma_f32_16x16x32_bf16 v[34:37], v[212:215], v[152:155], v[34:37]
	v_mfma_f32_16x16x32_bf16 v[30:33], v[188:191], v[156:159], v[30:33]
	v_mfma_f32_16x16x32_bf16 v[22:25], v[192:195], v[156:159], v[22:25]
	v_mfma_f32_16x16x32_bf16 v[26:29], v[208:211], v[156:159], v[26:29]
	v_mfma_f32_16x16x32_bf16 v[18:21], v[212:215], v[156:159], v[18:21]
	v_mfma_f32_16x16x32_bf16 v[14:17], v[188:191], v[160:163], v[14:17]
	v_mfma_f32_16x16x32_bf16 v[6:9], v[192:195], v[160:163], v[6:9]
	v_mfma_f32_16x16x32_bf16 v[10:13], v[208:211], v[160:163], v[10:13]
	v_mfma_f32_16x16x32_bf16 v[2:5], v[212:215], v[160:163], v[2:5]
	s_waitcnt lgkmcnt(0)
	v_mfma_f32_16x16x32_bf16 v[66:69], v[188:191], v[164:167], v[66:69]
	v_mfma_f32_16x16x32_bf16 v[70:73], v[192:195], v[164:167], v[70:73]
	v_mfma_f32_16x16x32_bf16 v[82:85], v[208:211], v[164:167], v[82:85]
	v_mfma_f32_16x16x32_bf16 v[86:89], v[212:215], v[164:167], v[86:89]
	v_mfma_f32_16x16x32_bf16 v[90:93], v[188:191], v[168:171], v[90:93]
	v_mfma_f32_16x16x32_bf16 v[94:97], v[192:195], v[168:171], v[94:97]
	v_mfma_f32_16x16x32_bf16 v[98:101], v[208:211], v[168:171], v[98:101]
	v_mfma_f32_16x16x32_bf16 v[102:105], v[212:215], v[168:171], v[102:105]
	v_mfma_f32_16x16x32_bf16 v[106:109], v[188:191], v[174:177], v[106:109]
	v_mfma_f32_16x16x32_bf16 v[110:113], v[192:195], v[174:177], v[110:113]
	v_mfma_f32_16x16x32_bf16 v[114:117], v[208:211], v[174:177], v[114:117]
	v_mfma_f32_16x16x32_bf16 v[118:121], v[212:215], v[174:177], v[118:121]
	v_mfma_f32_16x16x32_bf16 v[122:125], v[188:191], v[182:185], v[122:125]
	v_mfma_f32_16x16x32_bf16 v[126:129], v[192:195], v[182:185], v[126:129]
	v_mfma_f32_16x16x32_bf16 v[136:139], v[208:211], v[182:185], v[136:139]
	v_mfma_f32_16x16x32_bf16 v[140:143], v[212:215], v[182:185], v[140:143]
	s_setprio 0
	ds_read_b128 v[148:151], v81 offset:0
	ds_read_b128 v[152:155], v81 offset:2048
	ds_read_b128 v[156:159], v81 offset:4096
	ds_read_b128 v[160:163], v81 offset:6144
	ds_read_b128 v[188:191], v145 offset:49152
	ds_read_b128 v[192:195], v145 offset:51200
	ds_read_b128 v[208:211], v145 offset:53248
	ds_read_b128 v[212:215], v145 offset:55296
	ds_read_b128 v[164:167], v81 offset:16384
	ds_read_b128 v[168:171], v81 offset:18432
	ds_read_b128 v[174:177], v81 offset:20480
	ds_read_b128 v[182:185], v81 offset:22528
	s_setprio 1
	s_waitcnt lgkmcnt(4)
	v_mfma_f32_16x16x32_bf16 v[62:65], v[188:191], v[148:151], v[62:65]
	v_mfma_f32_16x16x32_bf16 v[54:57], v[192:195], v[148:151], v[54:57]
	v_mfma_f32_16x16x32_bf16 v[58:61], v[208:211], v[148:151], v[58:61]
	v_mfma_f32_16x16x32_bf16 v[50:53], v[212:215], v[148:151], v[50:53]
	v_mfma_f32_16x16x32_bf16 v[46:49], v[188:191], v[152:155], v[46:49]
	v_mfma_f32_16x16x32_bf16 v[38:41], v[192:195], v[152:155], v[38:41]
	v_mfma_f32_16x16x32_bf16 v[42:45], v[208:211], v[152:155], v[42:45]
	v_mfma_f32_16x16x32_bf16 v[34:37], v[212:215], v[152:155], v[34:37]
	v_mfma_f32_16x16x32_bf16 v[30:33], v[188:191], v[156:159], v[30:33]
	v_mfma_f32_16x16x32_bf16 v[22:25], v[192:195], v[156:159], v[22:25]
	v_mfma_f32_16x16x32_bf16 v[26:29], v[208:211], v[156:159], v[26:29]
	v_mfma_f32_16x16x32_bf16 v[18:21], v[212:215], v[156:159], v[18:21]
	v_mfma_f32_16x16x32_bf16 v[14:17], v[188:191], v[160:163], v[14:17]
	v_mfma_f32_16x16x32_bf16 v[6:9], v[192:195], v[160:163], v[6:9]
	v_mfma_f32_16x16x32_bf16 v[10:13], v[208:211], v[160:163], v[10:13]
	v_mfma_f32_16x16x32_bf16 v[2:5], v[212:215], v[160:163], v[2:5]
	s_waitcnt lgkmcnt(0)
	v_mfma_f32_16x16x32_bf16 v[66:69], v[188:191], v[164:167], v[66:69]
	v_mfma_f32_16x16x32_bf16 v[70:73], v[192:195], v[164:167], v[70:73]
	v_mfma_f32_16x16x32_bf16 v[82:85], v[208:211], v[164:167], v[82:85]
	v_mfma_f32_16x16x32_bf16 v[86:89], v[212:215], v[164:167], v[86:89]
	v_mfma_f32_16x16x32_bf16 v[90:93], v[188:191], v[168:171], v[90:93]
	v_mfma_f32_16x16x32_bf16 v[94:97], v[192:195], v[168:171], v[94:97]
	v_mfma_f32_16x16x32_bf16 v[98:101], v[208:211], v[168:171], v[98:101]
	v_mfma_f32_16x16x32_bf16 v[102:105], v[212:215], v[168:171], v[102:105]
	v_mfma_f32_16x16x32_bf16 v[106:109], v[188:191], v[174:177], v[106:109]
	v_mfma_f32_16x16x32_bf16 v[110:113], v[192:195], v[174:177], v[110:113]
	v_mfma_f32_16x16x32_bf16 v[114:117], v[208:211], v[174:177], v[114:117]
	v_mfma_f32_16x16x32_bf16 v[118:121], v[212:215], v[174:177], v[118:121]
	v_mfma_f32_16x16x32_bf16 v[122:125], v[188:191], v[182:185], v[122:125]
	v_mfma_f32_16x16x32_bf16 v[126:129], v[192:195], v[182:185], v[126:129]
	v_mfma_f32_16x16x32_bf16 v[136:139], v[208:211], v[182:185], v[136:139]
	v_mfma_f32_16x16x32_bf16 v[140:143], v[212:215], v[182:185], v[140:143]
	s_setprio 0
	s_nop 7
	s_nop 7
	s_nop 7
	s_add_i32 s48, s48, 1
	s_mov_b32 s39, 0
	v_readlane_b32 s30, v249, 0
	s_nop 0
	s_and_b32 s31, s30, 7
	s_lshr_b32 s30, s30, 3
	s_cmp_lt_u32 s30, 32
	s_cselect_b32 s35, 6, 5
	s_cmp_lt_u32 s48, s35
	s_cbranch_scc0 .Lf2_c1_extra
	s_lshl_b32 s33, s48, 6
	s_add_i32 s33, s33, s30
	s_cmp_ge_u32 s33, 0xb0
	s_cselect_b32 s34, 1, 0
	s_mul_i32 s36, s34, 0xb0
	s_sub_i32 s33, s33, s36
	s_lshr_b32 s37, s33, 2
	s_and_b32 s33, s33, 3
	s_lshl_b32 s34, s34, 3
	s_add_i32 s33, s33, s34
	s_lshl_b32 s33, s33, 3
	s_add_i32 s36, s33, s31
	s_add_i32 s38, s36, 32
	s_branch .Lf2_c1_have

.Lf2_nopf:
	s_load_dwordx2 s[40:41], s[84:85], 0x1c0
	v_lshrrev_b32_e32 v148, 7, v196
	v_and_b32_e32 v149, 15, v196
	v_lshl_or_b32 v148, v148, 6, v149
	v_mul_u32_u24_e32 v148, 0x1600, v148
	v_bfe_u32 v149, v196, 6, 1
	v_bfe_u32 v150, v196, 4, 2
	v_lshlrev_b32_e32 v149, 6, v149
	v_lshl_or_b32 v149, v150, 3, v149
	v_and_b32_e32 v150, 1, v150
	v_mul_u32_u24_e32 v150, 24, v150
	v_add3_u32 v156, v148, v149, v150
	v_add_u32_e32 v157, 0x16000, v156
	v_add_u32_e32 v158, 0x2c000, v156
	v_add_u32_e32 v159, 0x42000, v156
	s_waitcnt lgkmcnt(0)
	s_mul_i32 s30, s8, 0xb0000
	s_lshl_b32 s31, s21, 7
	s_add_i32 s30, s30, s31
	s_add_u32 s42, s40, s30
	s_addc_u32 s43, s41, 0
	v_mul_f32_e32 v148, 0xbfb8aa3b, v62
	v_mul_f32_e32 v149, 0xbfb8aa3b, v63
	v_mul_f32_e32 v150, 0xbfb8aa3b, v64
	v_mul_f32_e32 v151, 0xbfb8aa3b, v65
	v_exp_f32_e32 v148, v148
	v_exp_f32_e32 v149, v149
	v_exp_f32_e32 v150, v150
	v_exp_f32_e32 v151, v151
	v_add_f32_e32 v148, 1.0, v148
	v_add_f32_e32 v149, 1.0, v149
	v_add_f32_e32 v150, 1.0, v150
	v_add_f32_e32 v151, 1.0, v151
	v_rcp_f32_e32 v148, v148
	v_rcp_f32_e32 v149, v149
	v_rcp_f32_e32 v150, v150
	v_rcp_f32_e32 v151, v151
	s_nop 0
	v_pk_mul_f32 v[62:63], v[62:63], v[148:149]
	v_pk_mul_f32 v[64:65], v[64:65], v[150:151]
	v_pk_mul_f32 v[58:59], v[58:59], v[62:63]
	v_pk_mul_f32 v[60:61], v[60:61], v[64:65]
	v_mul_f32_e32 v148, 0xbfb8aa3b, v54
	v_mul_f32_e32 v149, 0xbfb8aa3b, v55
	v_mul_f32_e32 v150, 0xbfb8aa3b, v56
	v_mul_f32_e32 v151, 0xbfb8aa3b, v57
	v_exp_f32_e32 v148, v148
	v_exp_f32_e32 v149, v149
	v_exp_f32_e32 v150, v150
	v_exp_f32_e32 v151, v151
	v_add_f32_e32 v148, 1.0, v148
	v_add_f32_e32 v149, 1.0, v149
	v_add_f32_e32 v150, 1.0, v150
	v_add_f32_e32 v151, 1.0, v151
	v_rcp_f32_e32 v148, v148
	v_rcp_f32_e32 v149, v149
	v_rcp_f32_e32 v150, v150
	v_rcp_f32_e32 v151, v151
	s_nop 0
	v_pk_mul_f32 v[54:55], v[54:55], v[148:149]
	v_pk_mul_f32 v[56:57], v[56:57], v[150:151]
	v_pk_mul_f32 v[50:51], v[50:51], v[54:55]
	v_pk_mul_f32 v[52:53], v[52:53], v[56:57]
	v_cvt_pk_bf16_f32 v164, v58, v59
	v_cvt_pk_bf16_f32 v165, v60, v61
	v_cvt_pk_bf16_f32 v166, v50, v51
	v_cvt_pk_bf16_f32 v167, v52, v53
	s_nop 1
	v_permlane16_swap_b32 v164, v166
	v_permlane16_swap_b32 v165, v167
	s_nop 1
	global_store_dwordx4 v156, v[164:167], s[42:43]
	v_mul_f32_e32 v148, 0xbfb8aa3b, v46
	v_mul_f32_e32 v149, 0xbfb8aa3b, v47
	v_mul_f32_e32 v150, 0xbfb8aa3b, v48
	v_mul_f32_e32 v151, 0xbfb8aa3b, v49
	v_exp_f32_e32 v148, v148
	v_exp_f32_e32 v149, v149
	v_exp_f32_e32 v150, v150
	v_exp_f32_e32 v151, v151
	v_add_f32_e32 v148, 1.0, v148
	v_add_f32_e32 v149, 1.0, v149
	v_add_f32_e32 v150, 1.0, v150
	v_add_f32_e32 v151, 1.0, v151
	v_rcp_f32_e32 v148, v148
	v_rcp_f32_e32 v149, v149
	v_rcp_f32_e32 v150, v150
	v_rcp_f32_e32 v151, v151
	s_nop 0
	v_pk_mul_f32 v[46:47], v[46:47], v[148:149]
	v_pk_mul_f32 v[48:49], v[48:49], v[150:151]
	v_pk_mul_f32 v[42:43], v[42:43], v[46:47]
	v_pk_mul_f32 v[44:45], v[44:45], v[48:49]
	v_mul_f32_e32 v148, 0xbfb8aa3b, v38
	v_mul_f32_e32 v149, 0xbfb8aa3b, v39
	v_mul_f32_e32 v150, 0xbfb8aa3b, v40
	v_mul_f32_e32 v151, 0xbfb8aa3b, v41
	v_exp_f32_e32 v148, v148
	v_exp_f32_e32 v149, v149
	v_exp_f32_e32 v150, v150
	v_exp_f32_e32 v151, v151
	v_add_f32_e32 v148, 1.0, v148
	v_add_f32_e32 v149, 1.0, v149
	v_add_f32_e32 v150, 1.0, v150
	v_add_f32_e32 v151, 1.0, v151
	v_rcp_f32_e32 v148, v148
	v_rcp_f32_e32 v149, v149
	v_rcp_f32_e32 v150, v150
	v_rcp_f32_e32 v151, v151
	s_nop 0
	v_pk_mul_f32 v[38:39], v[38:39], v[148:149]
	v_pk_mul_f32 v[40:41], v[40:41], v[150:151]
	v_pk_mul_f32 v[34:35], v[34:35], v[38:39]
	v_pk_mul_f32 v[36:37], v[36:37], v[40:41]
	v_cvt_pk_bf16_f32 v168, v42, v43
	v_cvt_pk_bf16_f32 v169, v44, v45
	v_cvt_pk_bf16_f32 v170, v34, v35
	v_cvt_pk_bf16_f32 v171, v36, v37
	s_nop 1
	v_permlane16_swap_b32 v168, v170
	v_permlane16_swap_b32 v169, v171
	s_nop 1
	global_store_dwordx4 v157, v[168:171], s[42:43]
	v_mul_f32_e32 v148, 0xbfb8aa3b, v30
	v_mul_f32_e32 v149, 0xbfb8aa3b, v31
	v_mul_f32_e32 v150, 0xbfb8aa3b, v32
	v_mul_f32_e32 v151, 0xbfb8aa3b, v33
	v_exp_f32_e32 v148, v148
	v_exp_f32_e32 v149, v149
	v_exp_f32_e32 v150, v150
	v_exp_f32_e32 v151, v151
	v_add_f32_e32 v148, 1.0, v148
	v_add_f32_e32 v149, 1.0, v149
	v_add_f32_e32 v150, 1.0, v150
	v_add_f32_e32 v151, 1.0, v151
	v_rcp_f32_e32 v148, v148
	v_rcp_f32_e32 v149, v149
	v_rcp_f32_e32 v150, v150
	v_rcp_f32_e32 v151, v151
	s_nop 0
	v_pk_mul_f32 v[30:31], v[30:31], v[148:149]
	v_pk_mul_f32 v[32:33], v[32:33], v[150:151]
	v_pk_mul_f32 v[26:27], v[26:27], v[30:31]
	v_pk_mul_f32 v[28:29], v[28:29], v[32:33]
	v_mul_f32_e32 v148, 0xbfb8aa3b, v22
	v_mul_f32_e32 v149, 0xbfb8aa3b, v23
	v_mul_f32_e32 v150, 0xbfb8aa3b, v24
	v_mul_f32_e32 v151, 0xbfb8aa3b, v25
	v_exp_f32_e32 v148, v148
	v_exp_f32_e32 v149, v149
	v_exp_f32_e32 v150, v150
	v_exp_f32_e32 v151, v151
	v_add_f32_e32 v148, 1.0, v148
	v_add_f32_e32 v149, 1.0, v149
	v_add_f32_e32 v150, 1.0, v150
	v_add_f32_e32 v151, 1.0, v151
	v_rcp_f32_e32 v148, v148
	v_rcp_f32_e32 v149, v149
	v_rcp_f32_e32 v150, v150
	v_rcp_f32_e32 v151, v151
	s_nop 0
	v_pk_mul_f32 v[22:23], v[22:23], v[148:149]
	v_pk_mul_f32 v[24:25], v[24:25], v[150:151]
	v_pk_mul_f32 v[18:19], v[18:19], v[22:23]
	v_pk_mul_f32 v[20:21], v[20:21], v[24:25]
	v_cvt_pk_bf16_f32 v164, v26, v27
	v_cvt_pk_bf16_f32 v165, v28, v29
	v_cvt_pk_bf16_f32 v166, v18, v19
	v_cvt_pk_bf16_f32 v167, v20, v21
	s_nop 1
	v_permlane16_swap_b32 v164, v166
	v_permlane16_swap_b32 v165, v167
	s_nop 1
	global_store_dwordx4 v158, v[164:167], s[42:43]
	v_mul_f32_e32 v148, 0xbfb8aa3b, v14
	v_mul_f32_e32 v149, 0xbfb8aa3b, v15
	v_mul_f32_e32 v150, 0xbfb8aa3b, v16
	v_mul_f32_e32 v151, 0xbfb8aa3b, v17
	v_exp_f32_e32 v148, v148
	v_exp_f32_e32 v149, v149
	v_exp_f32_e32 v150, v150
	v_exp_f32_e32 v151, v151
	v_add_f32_e32 v148, 1.0, v148
	v_add_f32_e32 v149, 1.0, v149
	v_add_f32_e32 v150, 1.0, v150
	v_add_f32_e32 v151, 1.0, v151
	v_rcp_f32_e32 v148, v148
	v_rcp_f32_e32 v149, v149
	v_rcp_f32_e32 v150, v150
	v_rcp_f32_e32 v151, v151
	s_nop 0
	v_pk_mul_f32 v[14:15], v[14:15], v[148:149]
	v_pk_mul_f32 v[16:17], v[16:17], v[150:151]
	v_pk_mul_f32 v[10:11], v[10:11], v[14:15]
	v_pk_mul_f32 v[12:13], v[12:13], v[16:17]
	v_mul_f32_e32 v148, 0xbfb8aa3b, v6
	v_mul_f32_e32 v149, 0xbfb8aa3b, v7
	v_mul_f32_e32 v150, 0xbfb8aa3b, v8
	v_mul_f32_e32 v151, 0xbfb8aa3b, v9
	v_exp_f32_e32 v148, v148
	v_exp_f32_e32 v149, v149
	v_exp_f32_e32 v150, v150
	v_exp_f32_e32 v151, v151
	v_add_f32_e32 v148, 1.0, v148
	v_add_f32_e32 v149, 1.0, v149
	v_add_f32_e32 v150, 1.0, v150
	v_add_f32_e32 v151, 1.0, v151
	v_rcp_f32_e32 v148, v148
	v_rcp_f32_e32 v149, v149
	v_rcp_f32_e32 v150, v150
	v_rcp_f32_e32 v151, v151
	s_nop 0
	v_pk_mul_f32 v[6:7], v[6:7], v[148:149]
	v_pk_mul_f32 v[8:9], v[8:9], v[150:151]
	v_pk_mul_f32 v[2:3], v[2:3], v[6:7]
	v_pk_mul_f32 v[4:5], v[4:5], v[8:9]
	v_cvt_pk_bf16_f32 v168, v10, v11
	v_cvt_pk_bf16_f32 v169, v12, v13
	v_cvt_pk_bf16_f32 v170, v2, v3
	v_cvt_pk_bf16_f32 v171, v4, v5
	s_nop 1
	v_permlane16_swap_b32 v168, v170
	v_permlane16_swap_b32 v169, v171
	s_nop 1
	global_store_dwordx4 v159, v[168:171], s[42:43]
	s_mul_i32 s30, s49, 0xb0000
	s_lshl_b32 s31, s21, 7
	s_add_i32 s30, s30, s31
	s_add_u32 s42, s40, s30
	s_addc_u32 s43, s41, 0
	v_mul_f32_e32 v148, 0xbfb8aa3b, v66
	v_mul_f32_e32 v149, 0xbfb8aa3b, v67
	v_mul_f32_e32 v150, 0xbfb8aa3b, v68
	v_mul_f32_e32 v151, 0xbfb8aa3b, v69
	v_exp_f32_e32 v148, v148
	v_exp_f32_e32 v149, v149
	v_exp_f32_e32 v150, v150
	v_exp_f32_e32 v151, v151
	v_add_f32_e32 v148, 1.0, v148
	v_add_f32_e32 v149, 1.0, v149
	v_add_f32_e32 v150, 1.0, v150
	v_add_f32_e32 v151, 1.0, v151
	v_rcp_f32_e32 v148, v148
	v_rcp_f32_e32 v149, v149
	v_rcp_f32_e32 v150, v150
	v_rcp_f32_e32 v151, v151
	s_nop 0
	v_pk_mul_f32 v[66:67], v[66:67], v[148:149]
	v_pk_mul_f32 v[68:69], v[68:69], v[150:151]
	v_pk_mul_f32 v[82:83], v[82:83], v[66:67]
	v_pk_mul_f32 v[84:85], v[84:85], v[68:69]
	v_mul_f32_e32 v148, 0xbfb8aa3b, v70
	v_mul_f32_e32 v149, 0xbfb8aa3b, v71
	v_mul_f32_e32 v150, 0xbfb8aa3b, v72
	v_mul_f32_e32 v151, 0xbfb8aa3b, v73
	v_exp_f32_e32 v148, v148
	v_exp_f32_e32 v149, v149
	v_exp_f32_e32 v150, v150
	v_exp_f32_e32 v151, v151
	v_add_f32_e32 v148, 1.0, v148
	v_add_f32_e32 v149, 1.0, v149
	v_add_f32_e32 v150, 1.0, v150
	v_add_f32_e32 v151, 1.0, v151
	v_rcp_f32_e32 v148, v148
	v_rcp_f32_e32 v149, v149
	v_rcp_f32_e32 v150, v150
	v_rcp_f32_e32 v151, v151
	s_nop 0
	v_pk_mul_f32 v[70:71], v[70:71], v[148:149]
	v_pk_mul_f32 v[72:73], v[72:73], v[150:151]
	v_pk_mul_f32 v[86:87], v[86:87], v[70:71]
	v_pk_mul_f32 v[88:89], v[88:89], v[72:73]
	v_cvt_pk_bf16_f32 v164, v82, v83
	v_cvt_pk_bf16_f32 v165, v84, v85
	v_cvt_pk_bf16_f32 v166, v86, v87
	v_cvt_pk_bf16_f32 v167, v88, v89
	s_nop 1
	v_permlane16_swap_b32 v164, v166
	v_permlane16_swap_b32 v165, v167
	s_nop 1
	global_store_dwordx4 v156, v[164:167], s[42:43]
	v_mul_f32_e32 v148, 0xbfb8aa3b, v90
	v_mul_f32_e32 v149, 0xbfb8aa3b, v91
	v_mul_f32_e32 v150, 0xbfb8aa3b, v92
	v_mul_f32_e32 v151, 0xbfb8aa3b, v93
	v_exp_f32_e32 v148, v148
	v_exp_f32_e32 v149, v149
	v_exp_f32_e32 v150, v150
	v_exp_f32_e32 v151, v151
	v_add_f32_e32 v148, 1.0, v148
	v_add_f32_e32 v149, 1.0, v149
	v_add_f32_e32 v150, 1.0, v150
	v_add_f32_e32 v151, 1.0, v151
	v_rcp_f32_e32 v148, v148
	v_rcp_f32_e32 v149, v149
	v_rcp_f32_e32 v150, v150
	v_rcp_f32_e32 v151, v151
	s_nop 0
	v_pk_mul_f32 v[90:91], v[90:91], v[148:149]
	v_pk_mul_f32 v[92:93], v[92:93], v[150:151]
	v_pk_mul_f32 v[98:99], v[98:99], v[90:91]
	v_pk_mul_f32 v[100:101], v[100:101], v[92:93]
	v_mul_f32_e32 v148, 0xbfb8aa3b, v94
	v_mul_f32_e32 v149, 0xbfb8aa3b, v95
	v_mul_f32_e32 v150, 0xbfb8aa3b, v96
	v_mul_f32_e32 v151, 0xbfb8aa3b, v97
	v_exp_f32_e32 v148, v148
	v_exp_f32_e32 v149, v149
	v_exp_f32_e32 v150, v150
	v_exp_f32_e32 v151, v151
	v_add_f32_e32 v148, 1.0, v148
	v_add_f32_e32 v149, 1.0, v149
	v_add_f32_e32 v150, 1.0, v150
	v_add_f32_e32 v151, 1.0, v151
	v_rcp_f32_e32 v148, v148
	v_rcp_f32_e32 v149, v149
	v_rcp_f32_e32 v150, v150
	v_rcp_f32_e32 v151, v151
	s_nop 0
	v_pk_mul_f32 v[94:95], v[94:95], v[148:149]
	v_pk_mul_f32 v[96:97], v[96:97], v[150:151]
	v_pk_mul_f32 v[102:103], v[102:103], v[94:95]
	v_pk_mul_f32 v[104:105], v[104:105], v[96:97]
	v_cvt_pk_bf16_f32 v168, v98, v99
	v_cvt_pk_bf16_f32 v169, v100, v101
	v_cvt_pk_bf16_f32 v170, v102, v103
	v_cvt_pk_bf16_f32 v171, v104, v105
	s_nop 1
	v_permlane16_swap_b32 v168, v170
	v_permlane16_swap_b32 v169, v171
	s_nop 1
	global_store_dwordx4 v157, v[168:171], s[42:43]
	v_mul_f32_e32 v148, 0xbfb8aa3b, v106
	v_mul_f32_e32 v149, 0xbfb8aa3b, v107
	v_mul_f32_e32 v150, 0xbfb8aa3b, v108
	v_mul_f32_e32 v151, 0xbfb8aa3b, v109
	v_exp_f32_e32 v148, v148
	v_exp_f32_e32 v149, v149
	v_exp_f32_e32 v150, v150
	v_exp_f32_e32 v151, v151
	v_add_f32_e32 v148, 1.0, v148
	v_add_f32_e32 v149, 1.0, v149
	v_add_f32_e32 v150, 1.0, v150
	v_add_f32_e32 v151, 1.0, v151
	v_rcp_f32_e32 v148, v148
	v_rcp_f32_e32 v149, v149
	v_rcp_f32_e32 v150, v150
	v_rcp_f32_e32 v151, v151
	s_nop 0
	v_pk_mul_f32 v[106:107], v[106:107], v[148:149]
	v_pk_mul_f32 v[108:109], v[108:109], v[150:151]
	v_pk_mul_f32 v[114:115], v[114:115], v[106:107]
	v_pk_mul_f32 v[116:117], v[116:117], v[108:109]
	v_mul_f32_e32 v148, 0xbfb8aa3b, v110
	v_mul_f32_e32 v149, 0xbfb8aa3b, v111
	v_mul_f32_e32 v150, 0xbfb8aa3b, v112
	v_mul_f32_e32 v151, 0xbfb8aa3b, v113
	v_exp_f32_e32 v148, v148
	v_exp_f32_e32 v149, v149
	v_exp_f32_e32 v150, v150
	v_exp_f32_e32 v151, v151
	v_add_f32_e32 v148, 1.0, v148
	v_add_f32_e32 v149, 1.0, v149
	v_add_f32_e32 v150, 1.0, v150
	v_add_f32_e32 v151, 1.0, v151
	v_rcp_f32_e32 v148, v148
	v_rcp_f32_e32 v149, v149
	v_rcp_f32_e32 v150, v150
	v_rcp_f32_e32 v151, v151
	s_nop 0
	v_pk_mul_f32 v[110:111], v[110:111], v[148:149]
	v_pk_mul_f32 v[112:113], v[112:113], v[150:151]
	v_pk_mul_f32 v[118:119], v[118:119], v[110:111]
	v_pk_mul_f32 v[120:121], v[120:121], v[112:113]
	v_cvt_pk_bf16_f32 v164, v114, v115
	v_cvt_pk_bf16_f32 v165, v116, v117
	v_cvt_pk_bf16_f32 v166, v118, v119
	v_cvt_pk_bf16_f32 v167, v120, v121
	s_nop 1
	v_permlane16_swap_b32 v164, v166
	v_permlane16_swap_b32 v165, v167
	s_nop 1
	global_store_dwordx4 v158, v[164:167], s[42:43]
	v_mul_f32_e32 v148, 0xbfb8aa3b, v122
	v_mul_f32_e32 v149, 0xbfb8aa3b, v123
	v_mul_f32_e32 v150, 0xbfb8aa3b, v124
	v_mul_f32_e32 v151, 0xbfb8aa3b, v125
	v_exp_f32_e32 v148, v148
	v_exp_f32_e32 v149, v149
	v_exp_f32_e32 v150, v150
	v_exp_f32_e32 v151, v151
	v_add_f32_e32 v148, 1.0, v148
	v_add_f32_e32 v149, 1.0, v149
	v_add_f32_e32 v150, 1.0, v150
	v_add_f32_e32 v151, 1.0, v151
	v_rcp_f32_e32 v148, v148
	v_rcp_f32_e32 v149, v149
	v_rcp_f32_e32 v150, v150
	v_rcp_f32_e32 v151, v151
	s_nop 0
	v_pk_mul_f32 v[122:123], v[122:123], v[148:149]
	v_pk_mul_f32 v[124:125], v[124:125], v[150:151]
	v_pk_mul_f32 v[136:137], v[136:137], v[122:123]
	v_pk_mul_f32 v[138:139], v[138:139], v[124:125]
	v_mul_f32_e32 v148, 0xbfb8aa3b, v126
	v_mul_f32_e32 v149, 0xbfb8aa3b, v127
	v_mul_f32_e32 v150, 0xbfb8aa3b, v128
	v_mul_f32_e32 v151, 0xbfb8aa3b, v129
	v_exp_f32_e32 v148, v148
	v_exp_f32_e32 v149, v149
	v_exp_f32_e32 v150, v150
	v_exp_f32_e32 v151, v151
	v_add_f32_e32 v148, 1.0, v148
	v_add_f32_e32 v149, 1.0, v149
	v_add_f32_e32 v150, 1.0, v150
	v_add_f32_e32 v151, 1.0, v151
	v_rcp_f32_e32 v148, v148
	v_rcp_f32_e32 v149, v149
	v_rcp_f32_e32 v150, v150
	v_rcp_f32_e32 v151, v151
	s_nop 0
	v_pk_mul_f32 v[126:127], v[126:127], v[148:149]
	v_pk_mul_f32 v[128:129], v[128:129], v[150:151]
	v_pk_mul_f32 v[140:141], v[140:141], v[126:127]
	v_pk_mul_f32 v[142:143], v[142:143], v[128:129]
	v_cvt_pk_bf16_f32 v168, v136, v137
	v_cvt_pk_bf16_f32 v169, v138, v139
	v_cvt_pk_bf16_f32 v170, v140, v141
	v_cvt_pk_bf16_f32 v171, v142, v143
	s_nop 1
	v_permlane16_swap_b32 v168, v170
	v_permlane16_swap_b32 v169, v171
	s_nop 1
	global_store_dwordx4 v159, v[168:171], s[42:43]
